# seam barriers: non-leader workgroups wait on the top-level generation word directly (one release hop less)
# speedup vs baseline: 1.0103x; 1.0103x over previous
.LBB0_102:
	s_or_b64 exec, exec, s[14:15]
	v_cvt_f32_u32_e32 v4, v2
	s_waitcnt vmcnt(0)
	v_readfirstlane_b32 s3, v3
	v_sub_u32_e32 v3, 0, v2
	v_rcp_iflag_f32_e32 v4, v4
	v_add_u32_e32 v5, s3, v1
	v_mul_f32_e32 v4, 0x4f7ffffe, v4
	v_cvt_u32_f32_e32 v4, v4
	v_mul_lo_u32 v1, v3, v4
	v_mul_hi_u32 v1, v4, v1
	v_add_u32_e32 v1, v4, v1
	v_mul_hi_u32 v1, v5, v1
	v_mul_lo_u32 v3, v1, v2
	v_sub_u32_e32 v3, v5, v3
	v_add_u32_e32 v4, 1, v1
	v_cmp_ge_u32_e32 vcc, v3, v2
	s_nop 1
	v_cndmask_b32_e32 v1, v1, v4, vcc
	v_sub_u32_e32 v4, v3, v2
	v_cndmask_b32_e32 v3, v3, v4, vcc
	v_add_u32_e32 v4, 1, v1
	v_cmp_ge_u32_e32 vcc, v3, v2
	v_add_u32_e32 v3, 1, v5
	s_nop 0
	v_cndmask_b32_e32 v1, v1, v4, vcc
	v_mul_lo_u32 v4, v2, v1
	v_add_u32_e32 v2, v4, v2
	v_cmp_ne_u32_e32 vcc, v3, v2
	s_and_saveexec_b64 s[12:13], vcc
	s_xor_b64 s[12:13], exec, s[12:13]
	s_cbranch_execz .LBB0_116
	s_waitcnt lgkmcnt(0)
	buffer_inv sc1
	v_mov_b32_e32 v0, 0x3000
	global_load_dword v0, v0, s[8:9] offset:1280 sc1
	s_add_u32 s16, s8, 0x3500
	s_addc_u32 s17, s9, 0
	s_waitcnt vmcnt(0)
	v_cmp_eq_u32_e32 vcc, v0, v1
	s_and_saveexec_b64 s[14:15], vcc
	s_cbranch_execz .LBB0_115
	s_mov_b32 s3, 1
	s_mov_b64 s[20:21], 0
	v_mov_b32_e32 v0, 0
	s_branch .LBB0_106

.LBB0_202:
	s_or_b64 exec, exec, s[16:17]
	v_cvt_f32_u32_e32 v4, v2
	s_waitcnt vmcnt(0)
	v_readfirstlane_b32 s3, v3
	v_sub_u32_e32 v3, 0, v2
	v_rcp_iflag_f32_e32 v4, v4
	v_add_u32_e32 v5, s3, v1
	v_mul_f32_e32 v4, 0x4f7ffffe, v4
	v_cvt_u32_f32_e32 v4, v4
	v_mul_lo_u32 v1, v3, v4
	v_mul_hi_u32 v1, v4, v1
	v_add_u32_e32 v1, v4, v1
	v_mul_hi_u32 v1, v5, v1
	v_mul_lo_u32 v3, v1, v2
	v_sub_u32_e32 v3, v5, v3
	v_add_u32_e32 v4, 1, v1
	v_cmp_ge_u32_e32 vcc, v3, v2
	s_nop 1
	v_cndmask_b32_e32 v1, v1, v4, vcc
	v_sub_u32_e32 v4, v3, v2
	v_cndmask_b32_e32 v3, v3, v4, vcc
	v_add_u32_e32 v4, 1, v1
	v_cmp_ge_u32_e32 vcc, v3, v2
	v_add_u32_e32 v3, 1, v5
	s_nop 0
	v_cndmask_b32_e32 v1, v1, v4, vcc
	v_mul_lo_u32 v4, v2, v1
	v_add_u32_e32 v2, v4, v2
	v_cmp_ne_u32_e32 vcc, v3, v2
	s_and_saveexec_b64 s[14:15], vcc
	s_xor_b64 s[14:15], exec, s[14:15]
	s_cbranch_execz .LBB0_216
	s_waitcnt lgkmcnt(0)
	buffer_inv sc1
	v_mov_b32_e32 v0, 0x3000
	global_load_dword v0, v0, s[10:11] offset:1280 sc1
	s_add_u32 s20, s10, 0x3500
	s_addc_u32 s21, s11, 0
	s_waitcnt vmcnt(0)
	v_cmp_eq_u32_e32 vcc, v0, v1
	s_and_saveexec_b64 s[16:17], vcc
	s_cbranch_execz .LBB0_215
	s_mov_b32 s3, 1
	s_mov_b64 s[22:23], 0
	v_mov_b32_e32 v0, 0
	s_branch .LBB0_206

.LBB0_553:
	s_or_b64 exec, exec, s[20:21]
	v_cvt_f32_u32_e32 v4, v2
	s_waitcnt vmcnt(0)
	v_readfirstlane_b32 s3, v3
	v_sub_u32_e32 v3, 0, v2
	v_rcp_iflag_f32_e32 v4, v4
	v_add_u32_e32 v5, s3, v1
	v_mul_f32_e32 v4, 0x4f7ffffe, v4
	v_cvt_u32_f32_e32 v4, v4
	v_mul_lo_u32 v1, v3, v4
	v_mul_hi_u32 v1, v4, v1
	v_add_u32_e32 v1, v4, v1
	v_mul_hi_u32 v1, v5, v1
	v_mul_lo_u32 v3, v1, v2
	v_sub_u32_e32 v3, v5, v3
	v_add_u32_e32 v4, 1, v1
	v_cmp_ge_u32_e32 vcc, v3, v2
	s_nop 1
	v_cndmask_b32_e32 v1, v1, v4, vcc
	v_sub_u32_e32 v4, v3, v2
	v_cndmask_b32_e32 v3, v3, v4, vcc
	v_add_u32_e32 v4, 1, v1
	v_cmp_ge_u32_e32 vcc, v3, v2
	v_add_u32_e32 v3, 1, v5
	s_nop 0
	v_cndmask_b32_e32 v1, v1, v4, vcc
	v_mul_lo_u32 v4, v2, v1
	v_add_u32_e32 v2, v4, v2
	v_cmp_ne_u32_e32 vcc, v3, v2
	s_and_saveexec_b64 s[16:17], vcc
	s_xor_b64 s[16:17], exec, s[16:17]
	s_cbranch_execz .LBB0_567
	s_waitcnt lgkmcnt(0)
	buffer_inv sc1
	v_mov_b32_e32 v0, 0x3000
	global_load_dword v0, v0, s[12:13] offset:1280 sc1
	s_add_u32 s22, s12, 0x3500
	s_addc_u32 s23, s13, 0
	s_waitcnt vmcnt(0)
	v_cmp_eq_u32_e32 vcc, v0, v1
	s_and_saveexec_b64 s[20:21], vcc
	s_cbranch_execz .LBB0_566
	s_mov_b32 s3, 1
	s_mov_b64 s[24:25], 0
	v_mov_b32_e32 v0, 0
	s_branch .LBB0_557

.LBB0_1224:
	s_or_b64 exec, exec, s[12:13]
	v_cvt_f32_u32_e32 v4, v2
	s_waitcnt vmcnt(0)
	v_readfirstlane_b32 s3, v3
	v_sub_u32_e32 v3, 0, v2
	v_rcp_iflag_f32_e32 v4, v4
	v_add_u32_e32 v5, s3, v1
	v_mul_f32_e32 v4, 0x4f7ffffe, v4
	v_cvt_u32_f32_e32 v4, v4
	v_mul_lo_u32 v1, v3, v4
	v_mul_hi_u32 v1, v4, v1
	v_add_u32_e32 v1, v4, v1
	v_mul_hi_u32 v1, v5, v1
	v_mul_lo_u32 v3, v1, v2
	v_sub_u32_e32 v3, v5, v3
	v_add_u32_e32 v4, 1, v1
	v_cmp_ge_u32_e32 vcc, v3, v2
	s_nop 1
	v_cndmask_b32_e32 v1, v1, v4, vcc
	v_sub_u32_e32 v4, v3, v2
	v_cndmask_b32_e32 v3, v3, v4, vcc
	v_add_u32_e32 v4, 1, v1
	v_cmp_ge_u32_e32 vcc, v3, v2
	v_add_u32_e32 v3, 1, v5
	s_nop 0
	v_cndmask_b32_e32 v1, v1, v4, vcc
	v_mul_lo_u32 v4, v2, v1
	v_add_u32_e32 v2, v4, v2
	v_cmp_ne_u32_e32 vcc, v3, v2
	s_and_saveexec_b64 s[10:11], vcc
	s_xor_b64 s[10:11], exec, s[10:11]
	s_cbranch_execz .LBB0_1238
	s_waitcnt lgkmcnt(0)
	buffer_inv sc1
	v_mov_b32_e32 v0, 0x3000
	global_load_dword v0, v0, s[6:7] offset:1280 sc1
	s_add_u32 s14, s6, 0x3500
	s_addc_u32 s15, s7, 0
	s_waitcnt vmcnt(0)
	v_cmp_eq_u32_e32 vcc, v0, v1
	s_and_saveexec_b64 s[12:13], vcc
	s_cbranch_execz .LBB0_1237
	s_mov_b32 s3, 1
	s_mov_b64 s[16:17], 0
	v_mov_b32_e32 v0, 0
	s_branch .LBB0_1228
